# same stack with 8 wait states between each epilogue store and the next write of its data registers (P9 epilogue, P11 loop)
# speedup vs baseline: 1.0103x; 1.0103x over previous
.LBB0_633:
	v_lshl_add_u32 v0, s6, 8, v194
	v_ashrrev_i32_e32 v1, 31, v0
	v_lshl_add_u64 v[0:1], v[0:1], 2, s[12:13]
	s_nop 7
	s_lshl_b32 s0, s7, 7
	s_or_b32 s0, s0, s83
	s_ashr_i32 s0, s0, 6
	s_mul_hi_i32 s1, s6, 0x56
	s_mulk_i32 s6, 0x56
	s_ashr_i32 s7, s0, 31
	s_add_u32 s0, s6, s0
	s_addc_u32 s1, s1, s7
	v_pk_mul_f32 v[4:5], v[152:153], v[156:157]
	s_lshl_b64 s[0:1], s[0:1], 15
	v_pk_mul_f32 v[2:3], v[154:155], v[158:159]
	v_pk_mul_f32 v[6:7], v[150:151], v[146:147]
	v_pk_mul_f32 v[8:9], v[148:149], v[144:145]
	v_fmamk_f32 v10, v238, 0x3a000000, v200
	v_mul_f32_e32 v11, 0x4b800000, v10
	v_cmp_gt_f32_e32 vcc, s51, v10
	s_nop 1
	v_cndmask_b32_e32 v10, v10, v11, vcc
	v_rsq_f32_e32 v12, v10
	v_lshl_add_u64 v[10:11], v[170:171], 0, s[0:1]
	v_mul_f32_e32 v13, 0x45800000, v12
	v_cndmask_b32_e32 v12, v12, v13, vcc
	v_mul_f32_e32 v13, 0x3b800000, v12
	v_mul_f32_e32 v12, 0xbfb8aa3b, v13
	v_pk_mul_f32 v[16:17], v[152:153], v[12:13] op_sel_hi:[1,0]
	v_mul_f32_e32 v14, v13, v13
	v_pk_mul_f32 v[18:19], v[154:155], v[12:13] op_sel_hi:[1,0]
	v_pk_mul_f32 v[20:21], v[148:149], v[12:13] op_sel_hi:[1,0]
	v_pk_mul_f32 v[12:13], v[150:151], v[12:13] op_sel_hi:[1,0]
	v_exp_f32_e32 v16, v16
	v_exp_f32_e32 v17, v17
	v_exp_f32_e32 v18, v18
	v_exp_f32_e32 v19, v19
	v_exp_f32_e32 v20, v20
	v_exp_f32_e32 v21, v21
	v_exp_f32_e32 v12, v12
	v_exp_f32_e32 v13, v13
	v_pk_add_f32 v[16:17], v[16:17], 1.0 op_sel_hi:[1,0]
	v_pk_add_f32 v[18:19], v[18:19], 1.0 op_sel_hi:[1,0]
	v_pk_add_f32 v[20:21], v[20:21], 1.0 op_sel_hi:[1,0]
	v_pk_add_f32 v[12:13], v[12:13], 1.0 op_sel_hi:[1,0]
	v_rcp_f32_e32 v16, v16
	v_rcp_f32_e32 v17, v17
	v_rcp_f32_e32 v18, v18
	v_rcp_f32_e32 v19, v19
	v_rcp_f32_e32 v20, v20
	v_rcp_f32_e32 v21, v21
	v_rcp_f32_e32 v12, v12
	v_rcp_f32_e32 v13, v13
	v_pk_mul_f32 v[16:17], v[14:15], v[16:17] op_sel_hi:[0,1]
	v_pk_mul_f32 v[18:19], v[14:15], v[18:19] op_sel_hi:[0,1]
	v_pk_mul_f32 v[20:21], v[14:15], v[20:21] op_sel_hi:[0,1]
	v_pk_mul_f32 v[12:13], v[14:15], v[12:13] op_sel_hi:[0,1]
	v_pk_mul_f32 v[4:5], v[4:5], v[16:17]
	v_pk_mul_f32 v[14:15], v[2:3], v[18:19]
	v_pk_mul_f32 v[8:9], v[8:9], v[20:21]
	v_pk_mul_f32 v[6:7], v[6:7], v[12:13]
	v_cvt_pk_bf16_f32 v2, v4, v5
	v_cvt_pk_bf16_f32 v3, v14, v15
	v_cvt_pk_bf16_f32 v4, v8, v9
	v_pk_mul_f32 v[8:9], v[132:133], v[128:129]
	v_cvt_pk_bf16_f32 v5, v6, v7
	global_store_dwordx4 v[10:11], v[2:5], off nt
	s_nop 7
	v_lshl_add_u64 v[10:11], v[172:173], 0, s[0:1]
	v_pk_mul_f32 v[4:5], v[136:137], v[140:141]
	v_pk_mul_f32 v[2:3], v[138:139], v[142:143]
	v_fmamk_f32 v6, v239, 0x3a000000, v200
	v_mul_f32_e32 v7, 0x4b800000, v6
	v_cmp_gt_f32_e32 vcc, s51, v6
	s_nop 1
	v_cndmask_b32_e32 v6, v6, v7, vcc
	v_rsq_f32_e32 v12, v6
	v_pk_mul_f32 v[6:7], v[134:135], v[130:131]
	v_mul_f32_e32 v13, 0x45800000, v12
	v_cndmask_b32_e32 v12, v12, v13, vcc
	v_mul_f32_e32 v13, 0x3b800000, v12
	v_mul_f32_e32 v12, 0xbfb8aa3b, v13
	v_pk_mul_f32 v[16:17], v[136:137], v[12:13] op_sel_hi:[1,0]
	v_mul_f32_e32 v14, v13, v13
	v_pk_mul_f32 v[18:19], v[138:139], v[12:13] op_sel_hi:[1,0]
	v_pk_mul_f32 v[20:21], v[132:133], v[12:13] op_sel_hi:[1,0]
	v_pk_mul_f32 v[12:13], v[134:135], v[12:13] op_sel_hi:[1,0]
	v_exp_f32_e32 v16, v16
	v_exp_f32_e32 v17, v17
	v_exp_f32_e32 v18, v18
	v_exp_f32_e32 v19, v19
	v_exp_f32_e32 v20, v20
	v_exp_f32_e32 v21, v21
	v_exp_f32_e32 v12, v12
	v_exp_f32_e32 v13, v13
	v_pk_add_f32 v[16:17], v[16:17], 1.0 op_sel_hi:[1,0]
	v_pk_add_f32 v[18:19], v[18:19], 1.0 op_sel_hi:[1,0]
	v_pk_add_f32 v[20:21], v[20:21], 1.0 op_sel_hi:[1,0]
	v_pk_add_f32 v[12:13], v[12:13], 1.0 op_sel_hi:[1,0]
	v_rcp_f32_e32 v16, v16
	v_rcp_f32_e32 v17, v17
	v_rcp_f32_e32 v18, v18
	v_rcp_f32_e32 v19, v19
	v_rcp_f32_e32 v20, v20
	v_rcp_f32_e32 v21, v21
	v_rcp_f32_e32 v12, v12
	v_rcp_f32_e32 v13, v13
	v_pk_mul_f32 v[16:17], v[14:15], v[16:17] op_sel_hi:[0,1]
	v_pk_mul_f32 v[18:19], v[14:15], v[18:19] op_sel_hi:[0,1]
	v_pk_mul_f32 v[20:21], v[14:15], v[20:21] op_sel_hi:[0,1]
	v_pk_mul_f32 v[12:13], v[14:15], v[12:13] op_sel_hi:[0,1]
	v_pk_mul_f32 v[4:5], v[4:5], v[16:17]
	v_pk_mul_f32 v[14:15], v[2:3], v[18:19]
	v_pk_mul_f32 v[8:9], v[8:9], v[20:21]
	v_pk_mul_f32 v[6:7], v[6:7], v[12:13]
	v_cvt_pk_bf16_f32 v2, v4, v5
	v_cvt_pk_bf16_f32 v3, v14, v15
	v_cvt_pk_bf16_f32 v4, v8, v9
	v_pk_mul_f32 v[8:9], v[116:117], v[112:113]
	v_cvt_pk_bf16_f32 v5, v6, v7
	global_store_dwordx4 v[10:11], v[2:5], off nt
	s_nop 7
	v_lshl_add_u64 v[10:11], v[174:175], 0, s[0:1]
	v_pk_mul_f32 v[4:5], v[120:121], v[124:125]
	v_pk_mul_f32 v[2:3], v[122:123], v[126:127]
	v_fmamk_f32 v6, v240, 0x3a000000, v200
	v_mul_f32_e32 v7, 0x4b800000, v6
	v_cmp_gt_f32_e32 vcc, s51, v6
	s_nop 1
	v_cndmask_b32_e32 v6, v6, v7, vcc
	v_rsq_f32_e32 v12, v6
	v_pk_mul_f32 v[6:7], v[118:119], v[114:115]
	v_mul_f32_e32 v13, 0x45800000, v12
	v_cndmask_b32_e32 v12, v12, v13, vcc
	v_mul_f32_e32 v13, 0x3b800000, v12
	v_mul_f32_e32 v12, 0xbfb8aa3b, v13
	v_pk_mul_f32 v[16:17], v[120:121], v[12:13] op_sel_hi:[1,0]
	v_mul_f32_e32 v14, v13, v13
	v_pk_mul_f32 v[18:19], v[122:123], v[12:13] op_sel_hi:[1,0]
	v_pk_mul_f32 v[20:21], v[116:117], v[12:13] op_sel_hi:[1,0]
	v_pk_mul_f32 v[12:13], v[118:119], v[12:13] op_sel_hi:[1,0]
	v_exp_f32_e32 v16, v16
	v_exp_f32_e32 v17, v17
	v_exp_f32_e32 v18, v18
	v_exp_f32_e32 v19, v19
	v_exp_f32_e32 v20, v20
	v_exp_f32_e32 v21, v21
	v_exp_f32_e32 v12, v12
	v_exp_f32_e32 v13, v13
	v_pk_add_f32 v[16:17], v[16:17], 1.0 op_sel_hi:[1,0]
	v_pk_add_f32 v[18:19], v[18:19], 1.0 op_sel_hi:[1,0]
	v_pk_add_f32 v[20:21], v[20:21], 1.0 op_sel_hi:[1,0]
	v_pk_add_f32 v[12:13], v[12:13], 1.0 op_sel_hi:[1,0]
	v_rcp_f32_e32 v16, v16
	v_rcp_f32_e32 v17, v17
	v_rcp_f32_e32 v18, v18
	v_rcp_f32_e32 v19, v19
	v_rcp_f32_e32 v20, v20
	v_rcp_f32_e32 v21, v21
	v_rcp_f32_e32 v12, v12
	v_rcp_f32_e32 v13, v13
	v_pk_mul_f32 v[16:17], v[14:15], v[16:17] op_sel_hi:[0,1]
	v_pk_mul_f32 v[18:19], v[14:15], v[18:19] op_sel_hi:[0,1]
	v_pk_mul_f32 v[20:21], v[14:15], v[20:21] op_sel_hi:[0,1]
	v_pk_mul_f32 v[12:13], v[14:15], v[12:13] op_sel_hi:[0,1]
	v_pk_mul_f32 v[4:5], v[4:5], v[16:17]
	v_pk_mul_f32 v[14:15], v[2:3], v[18:19]
	v_pk_mul_f32 v[8:9], v[8:9], v[20:21]
	v_pk_mul_f32 v[6:7], v[6:7], v[12:13]
	v_cvt_pk_bf16_f32 v2, v4, v5
	v_cvt_pk_bf16_f32 v3, v14, v15
	v_cvt_pk_bf16_f32 v4, v8, v9
	v_pk_mul_f32 v[8:9], v[100:101], v[96:97]
	v_cvt_pk_bf16_f32 v5, v6, v7
	global_store_dwordx4 v[10:11], v[2:5], off nt
	s_nop 7
	v_lshl_add_u64 v[10:11], v[176:177], 0, s[0:1]
	v_pk_mul_f32 v[4:5], v[104:105], v[108:109]
	v_pk_mul_f32 v[2:3], v[106:107], v[110:111]
	s_add_u32 s0, s48, s0
	s_addc_u32 s1, s49, s1
	s_add_u32 s0, s0, 0x4000
	s_addc_u32 s1, s1, 0
	v_fmamk_f32 v6, v241, 0x3a000000, v200
	v_mul_f32_e32 v7, 0x4b800000, v6
	v_cmp_gt_f32_e32 vcc, s51, v6
	s_nop 1
	v_cndmask_b32_e32 v6, v6, v7, vcc
	v_rsq_f32_e32 v12, v6
	v_pk_mul_f32 v[6:7], v[102:103], v[98:99]
	v_mul_f32_e32 v13, 0x45800000, v12
	v_cndmask_b32_e32 v12, v12, v13, vcc
	v_mul_f32_e32 v13, 0x3b800000, v12
	v_mul_f32_e32 v12, 0xbfb8aa3b, v13
	v_pk_mul_f32 v[16:17], v[104:105], v[12:13] op_sel_hi:[1,0]
	v_mul_f32_e32 v14, v13, v13
	v_pk_mul_f32 v[18:19], v[106:107], v[12:13] op_sel_hi:[1,0]
	v_pk_mul_f32 v[20:21], v[100:101], v[12:13] op_sel_hi:[1,0]
	v_pk_mul_f32 v[12:13], v[102:103], v[12:13] op_sel_hi:[1,0]
	v_exp_f32_e32 v16, v16
	v_exp_f32_e32 v17, v17
	v_exp_f32_e32 v18, v18
	v_exp_f32_e32 v19, v19
	v_exp_f32_e32 v20, v20
	v_exp_f32_e32 v21, v21
	v_exp_f32_e32 v12, v12
	v_exp_f32_e32 v13, v13
	v_pk_add_f32 v[16:17], v[16:17], 1.0 op_sel_hi:[1,0]
	v_pk_add_f32 v[18:19], v[18:19], 1.0 op_sel_hi:[1,0]
	v_pk_add_f32 v[20:21], v[20:21], 1.0 op_sel_hi:[1,0]
	v_pk_add_f32 v[12:13], v[12:13], 1.0 op_sel_hi:[1,0]
	v_rcp_f32_e32 v16, v16
	v_rcp_f32_e32 v17, v17
	v_rcp_f32_e32 v18, v18
	v_rcp_f32_e32 v19, v19
	v_rcp_f32_e32 v20, v20
	v_rcp_f32_e32 v21, v21
	v_rcp_f32_e32 v12, v12
	v_rcp_f32_e32 v13, v13
	v_pk_mul_f32 v[16:17], v[14:15], v[16:17] op_sel_hi:[0,1]
	v_pk_mul_f32 v[18:19], v[14:15], v[18:19] op_sel_hi:[0,1]
	v_pk_mul_f32 v[20:21], v[14:15], v[20:21] op_sel_hi:[0,1]
	v_pk_mul_f32 v[12:13], v[14:15], v[12:13] op_sel_hi:[0,1]
	v_pk_mul_f32 v[4:5], v[4:5], v[16:17]
	v_pk_mul_f32 v[14:15], v[2:3], v[18:19]
	v_pk_mul_f32 v[8:9], v[8:9], v[20:21]
	v_pk_mul_f32 v[6:7], v[6:7], v[12:13]
	v_cvt_pk_bf16_f32 v2, v4, v5
	v_cvt_pk_bf16_f32 v3, v14, v15
	v_cvt_pk_bf16_f32 v4, v8, v9
	v_pk_mul_f32 v[8:9], v[84:85], v[80:81]
	v_cvt_pk_bf16_f32 v5, v6, v7
	global_store_dwordx4 v[10:11], v[2:5], off nt
	s_nop 7
	v_pk_mul_f32 v[6:7], v[86:87], v[82:83]
	v_pk_mul_f32 v[4:5], v[88:89], v[92:93]
	v_pk_mul_f32 v[2:3], v[90:91], v[94:95]
	v_fmamk_f32 v10, v242, 0x3a000000, v200
	v_mul_f32_e32 v11, 0x4b800000, v10
	v_cmp_gt_f32_e32 vcc, s51, v10
	s_nop 1
	v_cndmask_b32_e32 v10, v10, v11, vcc
	v_rsq_f32_e32 v12, v10
	v_lshl_add_u64 v[10:11], v[168:169], 1, s[0:1]
	v_mul_f32_e32 v13, 0x45800000, v12
	v_cndmask_b32_e32 v12, v12, v13, vcc
	v_mul_f32_e32 v13, 0x3b800000, v12
	v_mul_f32_e32 v12, 0xbfb8aa3b, v13
	v_pk_mul_f32 v[16:17], v[88:89], v[12:13] op_sel_hi:[1,0]
	v_mul_f32_e32 v14, v13, v13
	v_pk_mul_f32 v[18:19], v[90:91], v[12:13] op_sel_hi:[1,0]
	v_pk_mul_f32 v[20:21], v[84:85], v[12:13] op_sel_hi:[1,0]
	v_pk_mul_f32 v[12:13], v[86:87], v[12:13] op_sel_hi:[1,0]
	v_exp_f32_e32 v16, v16
	v_exp_f32_e32 v17, v17
	v_exp_f32_e32 v18, v18
	v_exp_f32_e32 v19, v19
	v_exp_f32_e32 v20, v20
	v_exp_f32_e32 v21, v21
	v_exp_f32_e32 v12, v12
	v_exp_f32_e32 v13, v13
	v_pk_add_f32 v[16:17], v[16:17], 1.0 op_sel_hi:[1,0]
	v_pk_add_f32 v[18:19], v[18:19], 1.0 op_sel_hi:[1,0]
	v_pk_add_f32 v[20:21], v[20:21], 1.0 op_sel_hi:[1,0]
	v_pk_add_f32 v[12:13], v[12:13], 1.0 op_sel_hi:[1,0]
	v_rcp_f32_e32 v16, v16
	v_rcp_f32_e32 v17, v17
	v_rcp_f32_e32 v18, v18
	v_rcp_f32_e32 v19, v19
	v_rcp_f32_e32 v20, v20
	v_rcp_f32_e32 v21, v21
	v_rcp_f32_e32 v12, v12
	v_rcp_f32_e32 v13, v13
	v_pk_mul_f32 v[16:17], v[14:15], v[16:17] op_sel_hi:[0,1]
	v_pk_mul_f32 v[18:19], v[14:15], v[18:19] op_sel_hi:[0,1]
	v_pk_mul_f32 v[20:21], v[14:15], v[20:21] op_sel_hi:[0,1]
	v_pk_mul_f32 v[12:13], v[14:15], v[12:13] op_sel_hi:[0,1]
	v_pk_mul_f32 v[4:5], v[4:5], v[16:17]
	v_pk_mul_f32 v[14:15], v[2:3], v[18:19]
	v_pk_mul_f32 v[8:9], v[8:9], v[20:21]
	v_pk_mul_f32 v[6:7], v[6:7], v[12:13]
	v_cvt_pk_bf16_f32 v2, v4, v5
	v_cvt_pk_bf16_f32 v3, v14, v15
	v_cvt_pk_bf16_f32 v4, v8, v9
	v_pk_mul_f32 v[8:9], v[68:69], v[64:65]
	v_cvt_pk_bf16_f32 v5, v6, v7
	global_store_dwordx4 v[10:11], v[2:5], off nt
	s_nop 7
	v_pk_mul_f32 v[6:7], v[70:71], v[66:67]
	v_pk_mul_f32 v[2:3], v[74:75], v[78:79]
	v_fmamk_f32 v4, v243, 0x3a000000, v200
	v_mul_f32_e32 v5, 0x4b800000, v4
	v_cmp_gt_f32_e32 vcc, s51, v4
	s_nop 1
	v_cndmask_b32_e32 v4, v4, v5, vcc
	v_rsq_f32_e32 v10, v4
	v_pk_mul_f32 v[4:5], v[72:73], v[76:77]
	v_mul_f32_e32 v11, 0x45800000, v10
	v_cndmask_b32_e32 v10, v10, v11, vcc
	v_mul_f32_e32 v11, 0x3b800000, v10
	v_mul_f32_e32 v10, 0xbfb8aa3b, v11
	v_pk_mul_f32 v[14:15], v[72:73], v[10:11] op_sel_hi:[1,0]
	v_mul_f32_e32 v12, v11, v11
	v_pk_mul_f32 v[16:17], v[74:75], v[10:11] op_sel_hi:[1,0]
	v_pk_mul_f32 v[18:19], v[68:69], v[10:11] op_sel_hi:[1,0]
	v_pk_mul_f32 v[10:11], v[70:71], v[10:11] op_sel_hi:[1,0]
	v_exp_f32_e32 v14, v14
	v_exp_f32_e32 v15, v15
	v_exp_f32_e32 v16, v16
	v_exp_f32_e32 v17, v17
	v_exp_f32_e32 v18, v18
	v_exp_f32_e32 v19, v19
	v_exp_f32_e32 v10, v10
	v_exp_f32_e32 v11, v11
	v_pk_add_f32 v[14:15], v[14:15], 1.0 op_sel_hi:[1,0]
	v_pk_add_f32 v[16:17], v[16:17], 1.0 op_sel_hi:[1,0]
	v_pk_add_f32 v[18:19], v[18:19], 1.0 op_sel_hi:[1,0]
	v_pk_add_f32 v[10:11], v[10:11], 1.0 op_sel_hi:[1,0]
	v_rcp_f32_e32 v14, v14
	v_rcp_f32_e32 v15, v15
	v_rcp_f32_e32 v16, v16
	v_rcp_f32_e32 v17, v17
	v_rcp_f32_e32 v18, v18
	v_rcp_f32_e32 v19, v19
	v_rcp_f32_e32 v10, v10
	v_rcp_f32_e32 v11, v11
	v_pk_mul_f32 v[14:15], v[12:13], v[14:15] op_sel_hi:[0,1]
	v_pk_mul_f32 v[16:17], v[12:13], v[16:17] op_sel_hi:[0,1]
	v_pk_mul_f32 v[18:19], v[12:13], v[18:19] op_sel_hi:[0,1]
	v_pk_mul_f32 v[10:11], v[12:13], v[10:11] op_sel_hi:[0,1]
	v_pk_mul_f32 v[4:5], v[4:5], v[14:15]
	v_pk_mul_f32 v[12:13], v[2:3], v[16:17]
	v_pk_mul_f32 v[8:9], v[8:9], v[18:19]
	v_pk_mul_f32 v[6:7], v[6:7], v[10:11]
	v_cvt_pk_bf16_f32 v2, v4, v5
	v_cvt_pk_bf16_f32 v3, v12, v13
	v_cvt_pk_bf16_f32 v4, v8, v9
	v_pk_mul_f32 v[8:9], v[52:53], v[48:49]
	v_cvt_pk_bf16_f32 v5, v6, v7
	global_store_dwordx4 v201, v[2:5], s[0:1] nt
	s_nop 7
	v_pk_mul_f32 v[6:7], v[54:55], v[50:51]
	v_pk_mul_f32 v[2:3], v[58:59], v[62:63]
	v_fmamk_f32 v4, v244, 0x3a000000, v200
	v_mul_f32_e32 v5, 0x4b800000, v4
	v_cmp_gt_f32_e32 vcc, s51, v4
	s_nop 1
	v_cndmask_b32_e32 v4, v4, v5, vcc
	v_rsq_f32_e32 v10, v4
	v_pk_mul_f32 v[4:5], v[56:57], v[60:61]
	v_mul_f32_e32 v11, 0x45800000, v10
	v_cndmask_b32_e32 v10, v10, v11, vcc
	v_mul_f32_e32 v11, 0x3b800000, v10
	v_mul_f32_e32 v10, 0xbfb8aa3b, v11
	v_pk_mul_f32 v[14:15], v[56:57], v[10:11] op_sel_hi:[1,0]
	v_mul_f32_e32 v12, v11, v11
	v_pk_mul_f32 v[16:17], v[58:59], v[10:11] op_sel_hi:[1,0]
	v_pk_mul_f32 v[18:19], v[52:53], v[10:11] op_sel_hi:[1,0]
	v_pk_mul_f32 v[10:11], v[54:55], v[10:11] op_sel_hi:[1,0]
	v_exp_f32_e32 v14, v14
	v_exp_f32_e32 v15, v15
	v_exp_f32_e32 v16, v16
	v_exp_f32_e32 v17, v17
	v_exp_f32_e32 v18, v18
	v_exp_f32_e32 v19, v19
	v_exp_f32_e32 v10, v10
	v_exp_f32_e32 v11, v11
	v_pk_add_f32 v[14:15], v[14:15], 1.0 op_sel_hi:[1,0]
	v_pk_add_f32 v[16:17], v[16:17], 1.0 op_sel_hi:[1,0]
	v_pk_add_f32 v[18:19], v[18:19], 1.0 op_sel_hi:[1,0]
	v_pk_add_f32 v[10:11], v[10:11], 1.0 op_sel_hi:[1,0]
	v_rcp_f32_e32 v14, v14
	v_rcp_f32_e32 v15, v15
	v_rcp_f32_e32 v16, v16
	v_rcp_f32_e32 v17, v17
	v_rcp_f32_e32 v18, v18
	v_rcp_f32_e32 v19, v19
	v_rcp_f32_e32 v10, v10
	v_rcp_f32_e32 v11, v11
	v_pk_mul_f32 v[14:15], v[12:13], v[14:15] op_sel_hi:[0,1]
	v_pk_mul_f32 v[16:17], v[12:13], v[16:17] op_sel_hi:[0,1]
	v_pk_mul_f32 v[18:19], v[12:13], v[18:19] op_sel_hi:[0,1]
	v_pk_mul_f32 v[10:11], v[12:13], v[10:11] op_sel_hi:[0,1]
	v_pk_mul_f32 v[4:5], v[4:5], v[14:15]
	v_pk_mul_f32 v[12:13], v[2:3], v[16:17]
	v_pk_mul_f32 v[8:9], v[8:9], v[18:19]
	v_pk_mul_f32 v[6:7], v[6:7], v[10:11]
	v_cvt_pk_bf16_f32 v2, v4, v5
	v_cvt_pk_bf16_f32 v3, v12, v13
	v_cvt_pk_bf16_f32 v4, v8, v9
	s_andn2_b64 vcc, exec, s[4:5]
	v_cvt_pk_bf16_f32 v5, v6, v7
	global_store_dwordx4 v202, v[2:5], s[0:1] nt
	s_nop 7
	v_pk_mul_f32 v[0:1], v[42:43], v[46:47]
	v_pk_mul_f32 v[2:3], v[40:41], v[44:45]
	v_pk_mul_f32 v[4:5], v[34:35], v[38:39]
	v_pk_mul_f32 v[6:7], v[32:33], v[36:37]
	v_fmamk_f32 v8, v245, 0x3a000000, v200
	v_mul_f32_e32 v9, 0x4b800000, v8
	v_cmp_gt_f32_e64 s[6:7], s51, v8
	s_nop 1
	v_cndmask_b32_e64 v8, v8, v9, s[6:7]
	v_rsq_f32_e32 v8, v8
	s_nop 0
	v_mul_f32_e32 v9, 0x45800000, v8
	v_cndmask_b32_e64 v8, v8, v9, s[6:7]
	v_mul_f32_e32 v9, 0x3b800000, v8
	v_mul_f32_e32 v8, 0xbfb8aa3b, v9
	v_pk_mul_f32 v[12:13], v[40:41], v[8:9] op_sel_hi:[1,0]
	v_mul_f32_e32 v10, v9, v9
	v_pk_mul_f32 v[14:15], v[42:43], v[8:9] op_sel_hi:[1,0]
	v_pk_mul_f32 v[16:17], v[32:33], v[8:9] op_sel_hi:[1,0]
	v_pk_mul_f32 v[8:9], v[34:35], v[8:9] op_sel_hi:[1,0]
	v_exp_f32_e32 v12, v12
	v_exp_f32_e32 v13, v13
	v_exp_f32_e32 v14, v14
	v_exp_f32_e32 v15, v15
	v_exp_f32_e32 v16, v16
	v_exp_f32_e32 v17, v17
	v_exp_f32_e32 v8, v8
	v_exp_f32_e32 v9, v9
	v_pk_add_f32 v[12:13], v[12:13], 1.0 op_sel_hi:[1,0]
	v_pk_add_f32 v[14:15], v[14:15], 1.0 op_sel_hi:[1,0]
	v_pk_add_f32 v[16:17], v[16:17], 1.0 op_sel_hi:[1,0]
	v_pk_add_f32 v[8:9], v[8:9], 1.0 op_sel_hi:[1,0]
	v_rcp_f32_e32 v12, v12
	v_rcp_f32_e32 v13, v13
	v_rcp_f32_e32 v14, v14
	v_rcp_f32_e32 v15, v15
	v_rcp_f32_e32 v16, v16
	v_rcp_f32_e32 v17, v17
	v_rcp_f32_e32 v8, v8
	v_rcp_f32_e32 v9, v9
	v_pk_mul_f32 v[12:13], v[10:11], v[12:13] op_sel_hi:[0,1]
	v_pk_mul_f32 v[14:15], v[10:11], v[14:15] op_sel_hi:[0,1]
	v_pk_mul_f32 v[16:17], v[10:11], v[16:17] op_sel_hi:[0,1]
	v_pk_mul_f32 v[8:9], v[10:11], v[8:9] op_sel_hi:[0,1]
	v_pk_mul_f32 v[2:3], v[2:3], v[12:13]
	v_pk_mul_f32 v[10:11], v[0:1], v[14:15]
	v_pk_mul_f32 v[6:7], v[6:7], v[16:17]
	v_pk_mul_f32 v[4:5], v[4:5], v[8:9]
	v_cvt_pk_bf16_f32 v0, v2, v3
	v_cvt_pk_bf16_f32 v1, v10, v11
	v_cvt_pk_bf16_f32 v2, v6, v7
	s_nop 0
	v_cvt_pk_bf16_f32 v3, v4, v5
	global_store_dwordx4 v203, v[0:3], s[0:1] nt
	s_mov_b64 s[0:1], -1
	s_cbranch_vccnz .LBB0_626
	s_andn2_b64 vcc, exec, s[8:9]
	s_cbranch_vccnz .LBB0_625
	s_barrier
	s_branch .LBB0_625

.LBB0_793:
	s_add_u32 s12, s78, s8
	s_addc_u32 s13, s79, s9
	s_nop 2
	global_load_dword v48, v42, s[12:13]
	v_lshl_add_u64 v[44:45], s[78:79], 0, v[40:41]
	v_add_co_u32_e32 v52, vcc, s11, v44
	v_lshl_add_u64 v[54:55], s[4:5], 0, v[32:33]
	s_nop 0
	v_addc_co_u32_e32 v53, vcc, 0, v45, vcc
	global_load_dwordx4 v[44:47], v[52:53], off
	global_load_dwordx4 v[62:65], v[52:53], off offset:1024
	global_load_dwordx4 v[66:69], v[52:53], off offset:2048
	global_load_dwordx4 v[70:73], v[52:53], off offset:3072
	s_add_i32 s80, s80, s82
	s_add_u32 s8, s8, s0
	s_addc_u32 s9, s9, s1
	v_lshl_add_u64 v[40:41], v[40:41], 0, s[2:3]
	s_waitcnt vmcnt(4)
	v_fmamk_f32 v56, v48, 0x3a000000, v43
	v_mul_f32_e32 v57, 0x4b800000, v56
	v_cmp_gt_f32_e32 vcc, s10, v56
	s_waitcnt vmcnt(3)
	v_lshlrev_b32_e32 v48, 16, v44
	v_cndmask_b32_e32 v56, v56, v57, vcc
	v_rsq_f32_e32 v56, v56
	v_and_b32_e32 v49, 0xffff0000, v44
	v_lshlrev_b32_e32 v44, 16, v45
	v_and_b32_e32 v45, 0xffff0000, v45
	v_mul_f32_e32 v57, 0x45800000, v56
	v_cndmask_b32_e32 v56, v56, v57, vcc
	v_lshlrev_b32_e32 v50, 16, v46
	v_and_b32_e32 v51, 0xffff0000, v46
	v_lshlrev_b32_e32 v46, 16, v47
	v_and_b32_e32 v47, 0xffff0000, v47
	v_pk_mul_f32 v[48:49], v[56:57], v[48:49] op_sel_hi:[0,1]
	v_pk_mul_f32 v[58:59], v[56:57], v[44:45] op_sel_hi:[0,1]
	v_pk_mul_f32 v[50:51], v[56:57], v[50:51] op_sel_hi:[0,1]
	v_pk_mul_f32 v[60:61], v[56:57], v[46:47] op_sel_hi:[0,1]
	v_pk_mul_f32 v[44:45], v[0:1], v[48:49]
	v_pk_mul_f32 v[46:47], v[2:3], v[58:59]
	v_pk_mul_f32 v[48:49], v[4:5], v[50:51]
	v_pk_mul_f32 v[50:51], v[6:7], v[60:61]
	global_store_dwordx4 v[54:55], v[44:47], off offset:-16 nt
	global_store_dwordx4 v[54:55], v[48:51], off nt
	s_nop 7
	v_lshl_add_u64 v[54:55], s[4:5], 0, v[34:35]
	s_waitcnt vmcnt(4)
	v_mov_b64_e32 v[44:45], v[62:63]
	v_mov_b64_e32 v[46:47], v[64:65]
	v_lshlrev_b32_e32 v48, 16, v44
	v_and_b32_e32 v49, 0xffff0000, v44
	v_lshlrev_b32_e32 v44, 16, v45
	v_and_b32_e32 v45, 0xffff0000, v45
	v_lshlrev_b32_e32 v50, 16, v46
	v_and_b32_e32 v51, 0xffff0000, v46
	v_lshlrev_b32_e32 v46, 16, v47
	v_and_b32_e32 v47, 0xffff0000, v47
	v_pk_mul_f32 v[48:49], v[56:57], v[48:49] op_sel_hi:[0,1]
	v_pk_mul_f32 v[58:59], v[56:57], v[44:45] op_sel_hi:[0,1]
	v_pk_mul_f32 v[50:51], v[56:57], v[50:51] op_sel_hi:[0,1]
	v_pk_mul_f32 v[60:61], v[56:57], v[46:47] op_sel_hi:[0,1]
	v_pk_mul_f32 v[44:45], v[8:9], v[48:49]
	v_pk_mul_f32 v[46:47], v[10:11], v[58:59]
	v_pk_mul_f32 v[48:49], v[12:13], v[50:51]
	v_pk_mul_f32 v[50:51], v[14:15], v[60:61]
	global_store_dwordx4 v[54:55], v[44:47], off offset:-16 nt
	global_store_dwordx4 v[54:55], v[48:51], off nt
	s_nop 7
	v_lshl_add_u64 v[54:55], s[4:5], 0, v[36:37]
	s_waitcnt vmcnt(5)
	v_mov_b64_e32 v[44:45], v[66:67]
	v_mov_b64_e32 v[46:47], v[68:69]
	v_lshlrev_b32_e32 v48, 16, v44
	v_and_b32_e32 v49, 0xffff0000, v44
	v_lshlrev_b32_e32 v44, 16, v45
	v_and_b32_e32 v45, 0xffff0000, v45
	v_lshlrev_b32_e32 v50, 16, v46
	v_and_b32_e32 v51, 0xffff0000, v46
	v_lshlrev_b32_e32 v46, 16, v47
	v_and_b32_e32 v47, 0xffff0000, v47
	v_pk_mul_f32 v[48:49], v[56:57], v[48:49] op_sel_hi:[0,1]
	v_pk_mul_f32 v[58:59], v[56:57], v[44:45] op_sel_hi:[0,1]
	v_pk_mul_f32 v[50:51], v[56:57], v[50:51] op_sel_hi:[0,1]
	v_pk_mul_f32 v[60:61], v[56:57], v[46:47] op_sel_hi:[0,1]
	v_pk_mul_f32 v[44:45], v[16:17], v[48:49]
	v_pk_mul_f32 v[46:47], v[18:19], v[58:59]
	v_pk_mul_f32 v[48:49], v[20:21], v[50:51]
	v_pk_mul_f32 v[50:51], v[22:23], v[60:61]
	global_store_dwordx4 v[54:55], v[44:47], off nt
	global_store_dwordx4 v[54:55], v[48:51], off offset:16 nt
	s_nop 7
	v_lshl_add_u64 v[52:53], s[4:5], 0, v[38:39]
	s_add_u32 s4, s4, s6
	s_addc_u32 s5, s5, s7
	s_cmpk_gt_i32 s80, 0x7fff
	s_waitcnt vmcnt(6)
	v_mov_b64_e32 v[44:45], v[70:71]
	v_mov_b64_e32 v[46:47], v[72:73]
	v_lshlrev_b32_e32 v48, 16, v44
	v_and_b32_e32 v49, 0xffff0000, v44
	v_lshlrev_b32_e32 v44, 16, v45
	v_and_b32_e32 v45, 0xffff0000, v45
	v_lshlrev_b32_e32 v50, 16, v46
	v_and_b32_e32 v51, 0xffff0000, v46
	v_lshlrev_b32_e32 v46, 16, v47
	v_and_b32_e32 v47, 0xffff0000, v47
	v_pk_mul_f32 v[48:49], v[56:57], v[48:49] op_sel_hi:[0,1]
	v_pk_mul_f32 v[54:55], v[56:57], v[44:45] op_sel_hi:[0,1]
	v_pk_mul_f32 v[50:51], v[56:57], v[50:51] op_sel_hi:[0,1]
	v_pk_mul_f32 v[56:57], v[56:57], v[46:47] op_sel_hi:[0,1]
	v_pk_mul_f32 v[44:45], v[24:25], v[48:49]
	v_pk_mul_f32 v[46:47], v[26:27], v[54:55]
	v_pk_mul_f32 v[48:49], v[28:29], v[50:51]
	v_pk_mul_f32 v[50:51], v[30:31], v[56:57]
	global_store_dwordx4 v[52:53], v[44:47], off nt
	global_store_dwordx4 v[52:53], v[48:51], off offset:16 nt
	s_cbranch_scc0 .LBB0_793
